# v91 + first B1 queue pop of each layer issued before the constant staging loads
# baseline (speedup 1.0000x reference)
.LBB0_317:
	s_and_b64 vcc, exec, s[0:1]
	s_cbranch_vccz .LBB0_502
	s_cmp_gt_i32 s78, 0
	s_mov_b64 s[0:1], -1
	s_cbranch_scc0 .LBB0_500
	v_mov_b32_e32 v8, v133
	s_mul_i32 s0, s76, 0x680
	v_and_b32_e32 v0, 0xffffffc0, v8
	v_and_b32_e32 v3, 63, v8
	v_lshl_add_u32 v2, s76, 9, v0
	v_or_b32_e32 v2, v2, v3
	v_lshlrev_b32_e32 v64, 2, v3
	v_ashrrev_i32_e32 v3, 31, v2
	s_ashr_i32 s1, s0, 31
	v_lshlrev_b64 v[2:3], 2, v[2:3]
	v_readlane_b32 s36, v215, 26
	s_lshl_b64 s[0:1], s[0:1], 2
	v_lshl_add_u64 v[6:7], s[16:17], 0, v[2:3]
	v_readlane_b32 s37, v215, 27
	s_add_u32 s74, s14, s0
	s_waitcnt vmcnt(0) lgkmcnt(0)
	s_barrier
	global_load_dword v9, v[6:7], off
	v_readlane_b32 s40, v215, 30
	v_readlane_b32 s41, v215, 31
	v_lshl_add_u64 v[6:7], s[36:37], 0, v[2:3]
	s_addc_u32 s75, s15, s1
	v_readlane_b32 s20, v216, 4
	v_readlane_b32 s21, v216, 5
	s_lshl_b32 s2, s76, 2
	v_cmp_eq_u32_e32 vcc, 0, v133
	s_add_u32 s20, s20, s2
	s_addc_u32 s21, s21, 0
	s_and_saveexec_b64 s[28:29], vcc
	v_mov_b32_e32 v205, 1
	global_atomic_add v205, v65, v205, s[20:21] sc0
	s_mov_b64 exec, s[28:29]
	v_ashrrev_i32_e32 v1, 31, v0
	v_readlane_b32 s42, v215, 32
	v_readlane_b32 s43, v215, 33
	v_readlane_b32 s44, v215, 34
	v_readlane_b32 s45, v215, 35
	global_load_dword v10, v[6:7], off
	v_lshl_add_u64 v[6:7], s[40:41], 0, v[2:3]
	v_lshl_add_u64 v[4:5], v[0:1], 2, s[74:75]
	global_load_dword v11, v[6:7], off
	v_lshl_add_u64 v[6:7], s[42:43], 0, v[2:3]
	v_lshl_add_u64 v[2:3], s[44:45], 0, v[2:3]
	v_lshl_add_u64 v[4:5], v[4:5], 0, v[64:65]
	global_load_dword v6, v[6:7], off
	s_nop 0
	global_load_dword v7, v[2:3], off
	global_load_dword v12, v[4:5], off
	global_load_dword v13, v[4:5], off offset:2048
	v_add_co_u32_e32 v2, vcc, 0x1000, v4
	s_lshl_b64 s[0:1], s[76:77], 2
	s_nop 0
	v_addc_co_u32_e32 v3, vcc, 0, v5, vcc
	global_load_dword v2, v[2:3], off
	v_lshlrev_b32_e32 v3, 5, v8
	v_and_b32_e32 v3, 0xfffff800, v3
	v_readlane_b32 s20, v216, 4
	v_readlane_b32 s38, v215, 28
	v_readlane_b32 s39, v215, 29
	s_mov_b64 s[36:37], s[76:77]
	v_add_u32_e32 v204, 0, v3
	v_readlane_b32 s21, v216, 5
	s_add_u32 s76, s20, s0
	v_add_u32_e32 v3, v204, v64
	s_addc_u32 s77, s21, s1
	v_cmp_eq_u32_e64 s[38:39], 0, v8
	v_readlane_b32 s46, v215, 36
	v_readlane_b32 s47, v215, 37
	v_readlane_b32 s48, v215, 38
	v_readlane_b32 s49, v215, 39
	v_readlane_b32 s50, v215, 40
	v_readlane_b32 s51, v215, 41
	s_waitcnt vmcnt(6)
	ds_write2st64_b32 v3, v9, v10 offset0:32 offset1:33
	s_waitcnt vmcnt(4)
	ds_write2st64_b32 v3, v11, v6 offset0:34 offset1:35
	s_waitcnt vmcnt(2)
	ds_write2st64_b32 v3, v7, v12 offset0:36 offset1:37
	s_waitcnt vmcnt(0)
	ds_write2st64_b32 v3, v13, v2 offset0:38 offset1:39
	s_waitcnt lgkmcnt(0)
	s_barrier
	s_and_saveexec_b64 s[0:1], s[38:39]
	s_cbranch_execz .LBB0_323
	s_mov_b64 s[28:29], exec
	v_mbcnt_lo_u32_b32 v2, s28, 0
	v_mbcnt_hi_u32_b32 v2, s29, v2
	v_cmp_eq_u32_e32 vcc, 0, v2
	s_and_saveexec_b64 s[20:21], vcc
	s_cbranch_execz .LBB0_322
	s_bcnt1_i32_b64 s2, s[28:29]
	v_mov_b32_e32 v3, s2
	v_mov_b32_e32 v3, v205
